# adds P1/P8 SwiGLU epilogue row-scale load batching (8 loads up front, no per-group vmcnt(0) drain) on top of P3 batched row scales + widened stores
# speedup vs baseline: 1.0213x; 1.0155x over previous
; __device__ __forceinline__ unsigned cvt_pk_bf16(float lo, float hi) { unsigned r; asm volatile("v_cvt_pk_bf16_f32 %0, %1, %2" : "=v"(r) : "v"(lo), "v"(hi)); return r; }
; __device__ __forceinline__ float sigmoidf_(float x) { return __builtin_amdgcn_rcpf(1.f + __builtin_amdgcn_exp2f(-x * LOG2E)); }
;     __device__ __forceinline__ void operator()(const f32x4 (&acc)[2][2][4][2], const pg8::Unit& u, int wr, int wc, int fr, int fq) const {
;     ...
;             for (int m = 0; m < 4; ++m) { const int row = row0 + ai * 128 + m * 16; const float rs = __builtin_amdgcn_rsqf(ss[row] * (1.f / DM) + EPS);
;                 float h[8];
; #pragma unroll
;                 for (int n = 0; n < 2; ++n)
; #pragma unroll
;                     for (int j = 0; j < 4; ++j) { const float g = acc[ai][0][m][n][j] * rs, up = acc[ai][1][m][n][j] * rs; h[4 * n + j] = g * sigmoidf_(g) * up; }
;                 u32x4 w; w.x = cvt_pk_bf16(h[0], h[1]); w.y = cvt_pk_bf16(h[2], h[3]); w.z = cvt_pk_bf16(h[4], h[5]); w.w = cvt_pk_bf16(h[6], h[7]);
;                 *(u32x4*)(H + (size_t)row * DFF + col0) = w; }
.LBB0_258:
	v_lshl_add_u32 v134, s44, 8, v233
	v_ashrrev_i32_e32 v135, 31, v134
	v_lshl_add_u64 v[136:137], v[134:135], 2, s[10:11]
	global_load_dword v160, v[136:137], off
	global_load_dword v161, v[136:137], off offset:64
	global_load_dword v162, v[136:137], off offset:128
	global_load_dword v163, v[136:137], off offset:192
	global_load_dword v164, v[136:137], off offset:512
	global_load_dword v165, v[136:137], off offset:576
	global_load_dword v166, v[136:137], off offset:640
	global_load_dword v167, v[136:137], off offset:704
	v_lshl_or_b32 v138, s42, 7, v235
	v_mov_b32_e32 v143, v124
	v_mov_b32_e32 v124, v121
	v_mov_b32_e32 v140, v130
	v_mov_b32_e32 v141, v126
	v_mov_b32_e32 v126, v131
	v_mov_b32_e32 v130, v132
	v_mov_b32_e32 v131, v128
	v_mov_b32_e32 v128, v133
	v_mov_b32_e32 v132, v118
	v_mov_b32_e32 v133, v122
	v_mov_b32_e32 v122, v119
	v_mov_b32_e32 v142, v120
	v_mov_b64_e32 v[118:119], s[18:19]
	v_ashrrev_i32_e32 v139, 31, v138
	v_mad_i64_i32 v[144:145], s[0:1], v134, s74, v[118:119]
	v_lshlrev_b64 v[120:121], 1, v[138:139]
	v_lshl_add_u64 v[138:139], v[144:145], 0, v[120:121]
	s_andn2_b64 vcc, exec, s[4:5]
	s_waitcnt vmcnt(7)
	v_mov_b32_e32 v0, v160
	v_fmamk_f32 v0, v0, 0x3a800000, v237
	v_rsq_f32_e32 v0, v0
	s_nop 0
	v_pk_mul_f32 v[124:125], v[124:125], v[0:1] op_sel_hi:[1,0]
	v_pk_mul_f32 v[140:141], v[140:141], v[0:1] op_sel_hi:[1,0]
	v_pk_mul_f32 v[126:127], v[126:127], v[0:1] op_sel_hi:[1,0]
	v_pk_mul_f32 v[130:131], v[130:131], v[0:1] op_sel_hi:[1,0]
	v_pk_mul_f32 v[128:129], v[128:129], v[0:1] op_sel_hi:[1,0]
	v_pk_mul_f32 v[132:133], v[132:133], v[0:1] op_sel_hi:[1,0]
	v_pk_mul_f32 v[122:123], v[122:123], v[0:1] op_sel_hi:[1,0]
	v_pk_mul_f32 v[142:143], v[142:143], v[0:1] op_sel_hi:[1,0]
	v_mul_f32_e32 v149, 0xbfb8aa3b, v125
	v_mul_f32_e32 v0, 0xbfb8aa3b, v141
	v_mul_f32_e32 v135, 0xbfb8aa3b, v127
	v_mul_f32_e32 v144, 0xbfb8aa3b, v131
	v_mul_f32_e32 v145, 0xbfb8aa3b, v129
	v_mul_f32_e32 v146, 0xbfb8aa3b, v133
	v_mul_f32_e32 v147, 0xbfb8aa3b, v123
	v_mul_f32_e32 v148, 0xbfb8aa3b, v143
	v_exp_f32_e32 v149, v149
	v_exp_f32_e32 v0, v0
	v_exp_f32_e32 v135, v135
	v_exp_f32_e32 v144, v144
	v_exp_f32_e32 v145, v145
	v_exp_f32_e32 v146, v146
	v_exp_f32_e32 v147, v147
	v_exp_f32_e32 v148, v148
	v_add_f32_e32 v149, 1.0, v149
	v_add_f32_e32 v0, 1.0, v0
	v_add_f32_e32 v135, 1.0, v135
	v_add_f32_e32 v144, 1.0, v144
	v_add_f32_e32 v145, 1.0, v145
	v_add_f32_e32 v146, 1.0, v146
	v_add_f32_e32 v147, 1.0, v147
	v_add_f32_e32 v148, 1.0, v148
	v_rcp_f32_e32 v149, v149
	v_rcp_f32_e32 v0, v0
	v_rcp_f32_e32 v135, v135
	v_rcp_f32_e32 v144, v144
	v_rcp_f32_e32 v145, v145
	v_rcp_f32_e32 v146, v146
	v_rcp_f32_e32 v147, v147
	v_rcp_f32_e32 v148, v148
	v_mul_f32_e32 v125, v125, v149
	v_mul_f32_e32 v0, v141, v0
	v_mul_f32_e32 v127, v127, v135
	v_mul_f32_e32 v131, v131, v144
	v_mul_f32_e32 v129, v129, v145
	v_mul_f32_e32 v133, v133, v146
	v_mul_f32_e32 v123, v123, v147
	v_mul_f32_e32 v135, v143, v148
	v_mul_f32_e32 v125, v124, v125
	v_mul_f32_e32 v0, v140, v0
	v_mul_f32_e32 v126, v126, v127
	v_mul_f32_e32 v127, v130, v131
	v_mul_f32_e32 v128, v128, v129
	v_mul_f32_e32 v129, v132, v133
	v_mul_f32_e32 v130, v122, v123
	v_mul_f32_e32 v131, v142, v135
	v_cvt_pk_bf16_f32 v122, v0, v126
	v_cvt_pk_bf16_f32 v123, v127, v128
	v_cvt_pk_bf16_f32 v124, v129, v130
	v_cvt_pk_bf16_f32 v125, v131, v125
	global_store_dwordx4 v[138:139], v[122:125], off
	s_waitcnt vmcnt(7)
	v_mov_b32_e32 v0, v161
	v_fmamk_f32 v0, v0, 0x3a800000, v237
	v_rsq_f32_e32 v0, v0
	v_mov_b32_e32 v122, v114
	v_mov_b32_e32 v114, v116
	v_mov_b32_e32 v116, v102
	v_mov_b32_e32 v102, v104
	v_or_b32_e32 v104, 16, v134
	v_mov_b32_e32 v123, v110
	v_mov_b32_e32 v110, v115
	v_mov_b32_e32 v115, v112
	v_mov_b32_e32 v112, v117
	v_mov_b32_e32 v117, v106
	v_mov_b32_e32 v106, v103
	v_mov_b32_e32 v103, v108
	v_mov_b32_e32 v108, v105
	v_mad_i64_i32 v[104:105], s[0:1], v104, s74, v[118:119]
	v_lshl_add_u64 v[124:125], v[104:105], 0, v[120:121]
	v_pk_mul_f32 v[104:105], v[122:123], v[0:1] op_sel_hi:[1,0]
	v_pk_mul_f32 v[110:111], v[110:111], v[0:1] op_sel_hi:[1,0]
	v_pk_mul_f32 v[114:115], v[114:115], v[0:1] op_sel_hi:[1,0]
	v_pk_mul_f32 v[112:113], v[112:113], v[0:1] op_sel_hi:[1,0]
	v_pk_mul_f32 v[116:117], v[116:117], v[0:1] op_sel_hi:[1,0]
	v_pk_mul_f32 v[106:107], v[106:107], v[0:1] op_sel_hi:[1,0]
	v_pk_mul_f32 v[102:103], v[102:103], v[0:1] op_sel_hi:[1,0]
	v_pk_mul_f32 v[108:109], v[108:109], v[0:1] op_sel_hi:[1,0]
	v_mul_f32_e32 v0, 0xbfb8aa3b, v105
	v_mul_f32_e32 v122, 0xbfb8aa3b, v111
	v_mul_f32_e32 v123, 0xbfb8aa3b, v115
	v_mul_f32_e32 v126, 0xbfb8aa3b, v113
	v_mul_f32_e32 v127, 0xbfb8aa3b, v117
	v_mul_f32_e32 v128, 0xbfb8aa3b, v107
	v_mul_f32_e32 v129, 0xbfb8aa3b, v103
	v_mul_f32_e32 v130, 0xbfb8aa3b, v109
	v_exp_f32_e32 v0, v0
	v_exp_f32_e32 v122, v122
	v_exp_f32_e32 v123, v123
	v_exp_f32_e32 v126, v126
	v_exp_f32_e32 v127, v127
	v_exp_f32_e32 v128, v128
	v_exp_f32_e32 v129, v129
	v_exp_f32_e32 v130, v130
	v_add_f32_e32 v0, 1.0, v0
	v_add_f32_e32 v122, 1.0, v122
	v_add_f32_e32 v123, 1.0, v123
	v_add_f32_e32 v126, 1.0, v126
	v_add_f32_e32 v127, 1.0, v127
	v_add_f32_e32 v128, 1.0, v128
	v_add_f32_e32 v129, 1.0, v129
	v_add_f32_e32 v130, 1.0, v130
	v_rcp_f32_e32 v0, v0
	v_rcp_f32_e32 v122, v122
	v_rcp_f32_e32 v123, v123
	v_rcp_f32_e32 v126, v126
	v_rcp_f32_e32 v127, v127
	v_rcp_f32_e32 v128, v128
	v_rcp_f32_e32 v129, v129
	v_rcp_f32_e32 v130, v130
	v_mul_f32_e32 v0, v105, v0
	v_mul_f32_e32 v105, v111, v122
	v_mul_f32_e32 v111, v115, v123
	v_mul_f32_e32 v113, v113, v126
	v_mul_f32_e32 v115, v117, v127
	v_mul_f32_e32 v107, v107, v128
	v_mul_f32_e32 v103, v103, v129
	v_mul_f32_e32 v109, v109, v130
	v_mul_f32_e32 v0, v104, v0
	v_mul_f32_e32 v104, v110, v105
	v_mul_f32_e32 v105, v114, v111
	v_mul_f32_e32 v110, v112, v113
	v_mul_f32_e32 v111, v116, v115
	v_mul_f32_e32 v106, v106, v107
	v_mul_f32_e32 v107, v102, v103
	v_mul_f32_e32 v108, v108, v109
	v_cvt_pk_bf16_f32 v102, v0, v104
	v_cvt_pk_bf16_f32 v103, v105, v110
	v_cvt_pk_bf16_f32 v104, v111, v106
	v_cvt_pk_bf16_f32 v105, v107, v108
	global_store_dwordx4 v[124:125], v[102:105], off
	s_waitcnt vmcnt(7)
; __device__ __forceinline__ unsigned cvt_pk_bf16(float lo, float hi) { unsigned r; asm volatile("v_cvt_pk_bf16_f32 %0, %1, %2" : "=v"(r) : "v"(lo), "v"(hi)); return r; }
; __device__ __forceinline__ float sigmoidf_(float x) { return __builtin_amdgcn_rcpf(1.f + __builtin_amdgcn_exp2f(-x * LOG2E)); }
;     __device__ __forceinline__ void operator()(const f32x4 (&acc)[2][2][4][2], const pg8::Unit& u, int wr, int wc, int fr, int fq) const {
;     ...
;             for (int m = 0; m < 4; ++m) { const int row = row0 + ai * 128 + m * 16; const float rs = __builtin_amdgcn_rsqf(ss[row] * (1.f / DM) + EPS);
;                 float h[8];
; #pragma unroll
;                 for (int n = 0; n < 2; ++n)
; #pragma unroll
;                     for (int j = 0; j < 4; ++j) { const float g = acc[ai][0][m][n][j] * rs, up = acc[ai][1][m][n][j] * rs; h[4 * n + j] = g * sigmoidf_(g) * up; }
;                 u32x4 w; w.x = cvt_pk_bf16(h[0], h[1]); w.y = cvt_pk_bf16(h[2], h[3]); w.z = cvt_pk_bf16(h[4], h[5]); w.w = cvt_pk_bf16(h[6], h[7]);
;                 *(u32x4*)(H + (size_t)row * DFF + col0) = w; }
	v_mov_b32_e32 v0, v162
	v_fmamk_f32 v0, v0, 0x3a800000, v237
	v_rsq_f32_e32 v0, v0
	v_mov_b32_e32 v102, v98
	v_mov_b32_e32 v98, v100
	v_mov_b32_e32 v100, v86
	v_mov_b32_e32 v86, v88
	v_or_b32_e32 v88, 32, v134
	v_mov_b32_e32 v103, v94
	v_mov_b32_e32 v94, v99
	v_mov_b32_e32 v99, v96
	v_mov_b32_e32 v96, v101
	v_mov_b32_e32 v101, v90
	v_mov_b32_e32 v90, v87
	v_mov_b32_e32 v87, v92
	v_mov_b32_e32 v92, v89
	v_mad_i64_i32 v[88:89], s[0:1], v88, s74, v[118:119]
	v_lshl_add_u64 v[104:105], v[88:89], 0, v[120:121]
	v_pk_mul_f32 v[88:89], v[102:103], v[0:1] op_sel_hi:[1,0]
	v_pk_mul_f32 v[94:95], v[94:95], v[0:1] op_sel_hi:[1,0]
	v_pk_mul_f32 v[98:99], v[98:99], v[0:1] op_sel_hi:[1,0]
	v_pk_mul_f32 v[96:97], v[96:97], v[0:1] op_sel_hi:[1,0]
	v_pk_mul_f32 v[100:101], v[100:101], v[0:1] op_sel_hi:[1,0]
	v_pk_mul_f32 v[90:91], v[90:91], v[0:1] op_sel_hi:[1,0]
	v_pk_mul_f32 v[86:87], v[86:87], v[0:1] op_sel_hi:[1,0]
	v_pk_mul_f32 v[92:93], v[92:93], v[0:1] op_sel_hi:[1,0]
	v_mul_f32_e32 v0, 0xbfb8aa3b, v89
	v_mul_f32_e32 v102, 0xbfb8aa3b, v95
	v_mul_f32_e32 v103, 0xbfb8aa3b, v99
	v_mul_f32_e32 v106, 0xbfb8aa3b, v97
	v_mul_f32_e32 v107, 0xbfb8aa3b, v101
	v_mul_f32_e32 v108, 0xbfb8aa3b, v91
	v_mul_f32_e32 v109, 0xbfb8aa3b, v87
	v_mul_f32_e32 v110, 0xbfb8aa3b, v93
	v_exp_f32_e32 v0, v0
	v_exp_f32_e32 v102, v102
	v_exp_f32_e32 v103, v103
	v_exp_f32_e32 v106, v106
	v_exp_f32_e32 v107, v107
	v_exp_f32_e32 v108, v108
	v_exp_f32_e32 v109, v109
	v_exp_f32_e32 v110, v110
	v_add_f32_e32 v0, 1.0, v0
	v_add_f32_e32 v102, 1.0, v102
	v_add_f32_e32 v103, 1.0, v103
	v_add_f32_e32 v106, 1.0, v106
	v_add_f32_e32 v107, 1.0, v107
	v_add_f32_e32 v108, 1.0, v108
	v_add_f32_e32 v109, 1.0, v109
	v_add_f32_e32 v110, 1.0, v110
	v_rcp_f32_e32 v0, v0
	v_rcp_f32_e32 v102, v102
	v_rcp_f32_e32 v103, v103
	v_rcp_f32_e32 v106, v106
	v_rcp_f32_e32 v107, v107
	v_rcp_f32_e32 v108, v108
	v_rcp_f32_e32 v109, v109
	v_rcp_f32_e32 v110, v110
	v_mul_f32_e32 v0, v89, v0
	v_mul_f32_e32 v89, v95, v102
	v_mul_f32_e32 v95, v99, v103
	v_mul_f32_e32 v97, v97, v106
	v_mul_f32_e32 v99, v101, v107
	v_mul_f32_e32 v91, v91, v108
	v_mul_f32_e32 v87, v87, v109
	v_mul_f32_e32 v93, v93, v110
	v_mul_f32_e32 v0, v88, v0
	v_mul_f32_e32 v88, v94, v89
	v_mul_f32_e32 v89, v98, v95
	v_mul_f32_e32 v94, v96, v97
	v_mul_f32_e32 v95, v100, v99
	v_mul_f32_e32 v90, v90, v91
	v_mul_f32_e32 v91, v86, v87
	v_mul_f32_e32 v92, v92, v93
	v_cvt_pk_bf16_f32 v86, v0, v88
	v_cvt_pk_bf16_f32 v87, v89, v94
	v_cvt_pk_bf16_f32 v88, v95, v90
	v_cvt_pk_bf16_f32 v89, v91, v92
	global_store_dwordx4 v[104:105], v[86:89], off
	s_waitcnt vmcnt(7)
	v_mov_b32_e32 v0, v163
	v_fmamk_f32 v0, v0, 0x3a800000, v237
	v_rsq_f32_e32 v0, v0
	v_mov_b32_e32 v86, v82
	v_mov_b32_e32 v82, v84
	v_mov_b32_e32 v84, v70
	v_mov_b32_e32 v70, v72
	v_or_b32_e32 v72, 48, v134
	v_mov_b32_e32 v87, v78
	v_mov_b32_e32 v78, v83
	v_mov_b32_e32 v83, v80
	v_mov_b32_e32 v80, v85
	v_mov_b32_e32 v85, v74
	v_mov_b32_e32 v74, v71
	v_mov_b32_e32 v71, v76
	v_mov_b32_e32 v76, v73
	v_mad_i64_i32 v[72:73], s[0:1], v72, s74, v[118:119]
	v_lshl_add_u64 v[88:89], v[72:73], 0, v[120:121]
	v_pk_mul_f32 v[72:73], v[86:87], v[0:1] op_sel_hi:[1,0]
	v_pk_mul_f32 v[78:79], v[78:79], v[0:1] op_sel_hi:[1,0]
	v_pk_mul_f32 v[82:83], v[82:83], v[0:1] op_sel_hi:[1,0]
	v_pk_mul_f32 v[80:81], v[80:81], v[0:1] op_sel_hi:[1,0]
	v_pk_mul_f32 v[84:85], v[84:85], v[0:1] op_sel_hi:[1,0]
	v_pk_mul_f32 v[74:75], v[74:75], v[0:1] op_sel_hi:[1,0]
	v_pk_mul_f32 v[70:71], v[70:71], v[0:1] op_sel_hi:[1,0]
	v_pk_mul_f32 v[76:77], v[76:77], v[0:1] op_sel_hi:[1,0]
	v_mul_f32_e32 v0, 0xbfb8aa3b, v73
	v_mul_f32_e32 v86, 0xbfb8aa3b, v79
	v_mul_f32_e32 v87, 0xbfb8aa3b, v83
	v_mul_f32_e32 v90, 0xbfb8aa3b, v81
	v_mul_f32_e32 v91, 0xbfb8aa3b, v85
	v_mul_f32_e32 v92, 0xbfb8aa3b, v75
	v_mul_f32_e32 v93, 0xbfb8aa3b, v71
	v_mul_f32_e32 v94, 0xbfb8aa3b, v77
	v_exp_f32_e32 v0, v0
	v_exp_f32_e32 v86, v86
	v_exp_f32_e32 v87, v87
	v_exp_f32_e32 v90, v90
	v_exp_f32_e32 v91, v91
	v_exp_f32_e32 v92, v92
	v_exp_f32_e32 v93, v93
	v_exp_f32_e32 v94, v94
	v_add_f32_e32 v0, 1.0, v0
	v_add_f32_e32 v86, 1.0, v86
	v_add_f32_e32 v87, 1.0, v87
	v_add_f32_e32 v90, 1.0, v90
	v_add_f32_e32 v91, 1.0, v91
	v_add_f32_e32 v92, 1.0, v92
	v_add_f32_e32 v93, 1.0, v93
	v_add_f32_e32 v94, 1.0, v94
	v_rcp_f32_e32 v0, v0
	v_rcp_f32_e32 v86, v86
	v_rcp_f32_e32 v87, v87
	v_rcp_f32_e32 v90, v90
	v_rcp_f32_e32 v91, v91
	v_rcp_f32_e32 v92, v92
	v_rcp_f32_e32 v93, v93
	v_rcp_f32_e32 v94, v94
	v_mul_f32_e32 v0, v73, v0
	v_mul_f32_e32 v73, v79, v86
	v_mul_f32_e32 v79, v83, v87
	v_mul_f32_e32 v81, v81, v90
	v_mul_f32_e32 v83, v85, v91
	v_mul_f32_e32 v75, v75, v92
	v_mul_f32_e32 v71, v71, v93
	v_mul_f32_e32 v77, v77, v94
	v_mul_f32_e32 v0, v72, v0
	v_mul_f32_e32 v72, v78, v73
	v_mul_f32_e32 v73, v82, v79
	v_mul_f32_e32 v78, v80, v81
	v_mul_f32_e32 v79, v84, v83
	v_mul_f32_e32 v74, v74, v75
	v_mul_f32_e32 v75, v70, v71
	v_mul_f32_e32 v76, v76, v77
	v_cvt_pk_bf16_f32 v70, v0, v72
	v_cvt_pk_bf16_f32 v71, v73, v78
	v_cvt_pk_bf16_f32 v72, v79, v74
	v_cvt_pk_bf16_f32 v73, v75, v76
	global_store_dwordx4 v[88:89], v[70:73], off
	s_waitcnt vmcnt(7)
; __device__ __forceinline__ unsigned cvt_pk_bf16(float lo, float hi) { unsigned r; asm volatile("v_cvt_pk_bf16_f32 %0, %1, %2" : "=v"(r) : "v"(lo), "v"(hi)); return r; }
; __device__ __forceinline__ float sigmoidf_(float x) { return __builtin_amdgcn_rcpf(1.f + __builtin_amdgcn_exp2f(-x * LOG2E)); }
;     __device__ __forceinline__ void operator()(const f32x4 (&acc)[2][2][4][2], const pg8::Unit& u, int wr, int wc, int fr, int fq) const {
;     ...
;             for (int m = 0; m < 4; ++m) { const int row = row0 + ai * 128 + m * 16; const float rs = __builtin_amdgcn_rsqf(ss[row] * (1.f / DM) + EPS);
;                 float h[8];
; #pragma unroll
;                 for (int n = 0; n < 2; ++n)
; #pragma unroll
;                     for (int j = 0; j < 4; ++j) { const float g = acc[ai][0][m][n][j] * rs, up = acc[ai][1][m][n][j] * rs; h[4 * n + j] = g * sigmoidf_(g) * up; }
;                 u32x4 w; w.x = cvt_pk_bf16(h[0], h[1]); w.y = cvt_pk_bf16(h[2], h[3]); w.z = cvt_pk_bf16(h[4], h[5]); w.w = cvt_pk_bf16(h[6], h[7]);
;                 *(u32x4*)(H + (size_t)row * DFF + col0) = w; }
	v_mov_b32_e32 v0, v164
	v_fmamk_f32 v0, v0, 0x3a800000, v237
	v_rsq_f32_e32 v0, v0
	v_mov_b32_e32 v70, v66
	v_mov_b32_e32 v66, v68
	v_mov_b32_e32 v68, v54
	v_mov_b32_e32 v54, v56
	v_add_u32_e32 v56, 0x80, v134
	v_mov_b32_e32 v71, v62
	v_mov_b32_e32 v62, v67
	v_mov_b32_e32 v67, v64
	v_mov_b32_e32 v64, v69
	v_mov_b32_e32 v69, v58
	v_mov_b32_e32 v58, v55
	v_mov_b32_e32 v55, v60
	v_mov_b32_e32 v60, v57
	v_mad_i64_i32 v[56:57], s[0:1], v56, s74, v[118:119]
	v_lshl_add_u64 v[72:73], v[56:57], 0, v[120:121]
	v_pk_mul_f32 v[56:57], v[70:71], v[0:1] op_sel_hi:[1,0]
	v_pk_mul_f32 v[62:63], v[62:63], v[0:1] op_sel_hi:[1,0]
	v_pk_mul_f32 v[66:67], v[66:67], v[0:1] op_sel_hi:[1,0]
	v_pk_mul_f32 v[64:65], v[64:65], v[0:1] op_sel_hi:[1,0]
	v_pk_mul_f32 v[68:69], v[68:69], v[0:1] op_sel_hi:[1,0]
	v_pk_mul_f32 v[58:59], v[58:59], v[0:1] op_sel_hi:[1,0]
	v_pk_mul_f32 v[54:55], v[54:55], v[0:1] op_sel_hi:[1,0]
	v_pk_mul_f32 v[60:61], v[60:61], v[0:1] op_sel_hi:[1,0]
	v_mul_f32_e32 v0, 0xbfb8aa3b, v57
	v_mul_f32_e32 v70, 0xbfb8aa3b, v63
	v_mul_f32_e32 v71, 0xbfb8aa3b, v67
	v_mul_f32_e32 v74, 0xbfb8aa3b, v65
	v_mul_f32_e32 v75, 0xbfb8aa3b, v69
	v_mul_f32_e32 v76, 0xbfb8aa3b, v59
	v_mul_f32_e32 v77, 0xbfb8aa3b, v55
	v_mul_f32_e32 v78, 0xbfb8aa3b, v61
	v_exp_f32_e32 v0, v0
	v_exp_f32_e32 v70, v70
	v_exp_f32_e32 v71, v71
	v_exp_f32_e32 v74, v74
	v_exp_f32_e32 v75, v75
	v_exp_f32_e32 v76, v76
	v_exp_f32_e32 v77, v77
	v_exp_f32_e32 v78, v78
	v_add_f32_e32 v0, 1.0, v0
	v_add_f32_e32 v70, 1.0, v70
	v_add_f32_e32 v71, 1.0, v71
	v_add_f32_e32 v74, 1.0, v74
	v_add_f32_e32 v75, 1.0, v75
	v_add_f32_e32 v76, 1.0, v76
	v_add_f32_e32 v77, 1.0, v77
	v_add_f32_e32 v78, 1.0, v78
	v_rcp_f32_e32 v0, v0
	v_rcp_f32_e32 v70, v70
	v_rcp_f32_e32 v71, v71
	v_rcp_f32_e32 v74, v74
	v_rcp_f32_e32 v75, v75
	v_rcp_f32_e32 v76, v76
	v_rcp_f32_e32 v77, v77
	v_rcp_f32_e32 v78, v78
	v_mul_f32_e32 v0, v57, v0
	v_mul_f32_e32 v57, v63, v70
	v_mul_f32_e32 v63, v67, v71
	v_mul_f32_e32 v65, v65, v74
	v_mul_f32_e32 v67, v69, v75
	v_mul_f32_e32 v59, v59, v76
	v_mul_f32_e32 v55, v55, v77
	v_mul_f32_e32 v61, v61, v78
	v_mul_f32_e32 v0, v56, v0
	v_mul_f32_e32 v56, v62, v57
	v_mul_f32_e32 v57, v66, v63
	v_mul_f32_e32 v62, v64, v65
	v_mul_f32_e32 v63, v68, v67
	v_mul_f32_e32 v58, v58, v59
	v_mul_f32_e32 v59, v54, v55
	v_mul_f32_e32 v60, v60, v61
	v_cvt_pk_bf16_f32 v54, v0, v56
	v_cvt_pk_bf16_f32 v55, v57, v62
	v_cvt_pk_bf16_f32 v56, v63, v58
	v_cvt_pk_bf16_f32 v57, v59, v60
	global_store_dwordx4 v[72:73], v[54:57], off
	s_waitcnt vmcnt(7)
	v_mov_b32_e32 v0, v165
	v_fmamk_f32 v0, v0, 0x3a800000, v237
	v_rsq_f32_e32 v0, v0
	v_mov_b32_e32 v54, v50
	v_mov_b32_e32 v50, v52
	v_mov_b32_e32 v52, v38
	v_mov_b32_e32 v38, v40
	v_add_u32_e32 v40, 0x90, v134
	v_mov_b32_e32 v55, v46
	v_mov_b32_e32 v46, v51
	v_mov_b32_e32 v51, v48
	v_mov_b32_e32 v48, v53
	v_mov_b32_e32 v53, v42
	v_mov_b32_e32 v42, v39
	v_mov_b32_e32 v39, v44
	v_mov_b32_e32 v44, v41
	v_mad_i64_i32 v[40:41], s[0:1], v40, s74, v[118:119]
	v_lshl_add_u64 v[56:57], v[40:41], 0, v[120:121]
	v_pk_mul_f32 v[40:41], v[54:55], v[0:1] op_sel_hi:[1,0]
	v_pk_mul_f32 v[46:47], v[46:47], v[0:1] op_sel_hi:[1,0]
	v_pk_mul_f32 v[50:51], v[50:51], v[0:1] op_sel_hi:[1,0]
	v_pk_mul_f32 v[48:49], v[48:49], v[0:1] op_sel_hi:[1,0]
	v_pk_mul_f32 v[52:53], v[52:53], v[0:1] op_sel_hi:[1,0]
	v_pk_mul_f32 v[42:43], v[42:43], v[0:1] op_sel_hi:[1,0]
	v_pk_mul_f32 v[38:39], v[38:39], v[0:1] op_sel_hi:[1,0]
	v_pk_mul_f32 v[44:45], v[44:45], v[0:1] op_sel_hi:[1,0]
	v_mul_f32_e32 v0, 0xbfb8aa3b, v41
	v_mul_f32_e32 v54, 0xbfb8aa3b, v47
	v_mul_f32_e32 v55, 0xbfb8aa3b, v51
	v_mul_f32_e32 v58, 0xbfb8aa3b, v49
	v_mul_f32_e32 v59, 0xbfb8aa3b, v53
	v_mul_f32_e32 v60, 0xbfb8aa3b, v43
	v_mul_f32_e32 v61, 0xbfb8aa3b, v39
	v_mul_f32_e32 v62, 0xbfb8aa3b, v45
	v_exp_f32_e32 v0, v0
	v_exp_f32_e32 v54, v54
	v_exp_f32_e32 v55, v55
	v_exp_f32_e32 v58, v58
	v_exp_f32_e32 v59, v59
	v_exp_f32_e32 v60, v60
	v_exp_f32_e32 v61, v61
	v_exp_f32_e32 v62, v62
	v_add_f32_e32 v0, 1.0, v0
	v_add_f32_e32 v54, 1.0, v54
	v_add_f32_e32 v55, 1.0, v55
	v_add_f32_e32 v58, 1.0, v58
	v_add_f32_e32 v59, 1.0, v59
	v_add_f32_e32 v60, 1.0, v60
	v_add_f32_e32 v61, 1.0, v61
	v_add_f32_e32 v62, 1.0, v62
	v_rcp_f32_e32 v0, v0
	v_rcp_f32_e32 v54, v54
	v_rcp_f32_e32 v55, v55
	v_rcp_f32_e32 v58, v58
	v_rcp_f32_e32 v59, v59
	v_rcp_f32_e32 v60, v60
	v_rcp_f32_e32 v61, v61
	v_rcp_f32_e32 v62, v62
	v_mul_f32_e32 v0, v41, v0
	v_mul_f32_e32 v41, v47, v54
	v_mul_f32_e32 v47, v51, v55
	v_mul_f32_e32 v49, v49, v58
	v_mul_f32_e32 v51, v53, v59
	v_mul_f32_e32 v43, v43, v60
	v_mul_f32_e32 v39, v39, v61
	v_mul_f32_e32 v45, v45, v62
	v_mul_f32_e32 v0, v40, v0
	v_mul_f32_e32 v40, v46, v41
	v_mul_f32_e32 v41, v50, v47
	v_mul_f32_e32 v46, v48, v49
	v_mul_f32_e32 v47, v52, v51
	v_mul_f32_e32 v42, v42, v43
	v_mul_f32_e32 v43, v38, v39
	v_mul_f32_e32 v44, v44, v45
	v_cvt_pk_bf16_f32 v38, v0, v40
	v_cvt_pk_bf16_f32 v39, v41, v46
	v_cvt_pk_bf16_f32 v40, v47, v42
	v_cvt_pk_bf16_f32 v41, v43, v44
	global_store_dwordx4 v[56:57], v[38:41], off
	s_waitcnt vmcnt(7)
; __device__ __forceinline__ unsigned cvt_pk_bf16(float lo, float hi) { unsigned r; asm volatile("v_cvt_pk_bf16_f32 %0, %1, %2" : "=v"(r) : "v"(lo), "v"(hi)); return r; }
; __device__ __forceinline__ float sigmoidf_(float x) { return __builtin_amdgcn_rcpf(1.f + __builtin_amdgcn_exp2f(-x * LOG2E)); }
;     __device__ __forceinline__ void operator()(const f32x4 (&acc)[2][2][4][2], const pg8::Unit& u, int wr, int wc, int fr, int fq) const {
;     ...
;             for (int m = 0; m < 4; ++m) { const int row = row0 + ai * 128 + m * 16; const float rs = __builtin_amdgcn_rsqf(ss[row] * (1.f / DM) + EPS);
;                 float h[8];
; #pragma unroll
;                 for (int n = 0; n < 2; ++n)
; #pragma unroll
;                     for (int j = 0; j < 4; ++j) { const float g = acc[ai][0][m][n][j] * rs, up = acc[ai][1][m][n][j] * rs; h[4 * n + j] = g * sigmoidf_(g) * up; }
;                 u32x4 w; w.x = cvt_pk_bf16(h[0], h[1]); w.y = cvt_pk_bf16(h[2], h[3]); w.z = cvt_pk_bf16(h[4], h[5]); w.w = cvt_pk_bf16(h[6], h[7]);
;                 *(u32x4*)(H + (size_t)row * DFF + col0) = w; }
	v_mov_b32_e32 v0, v166
	v_fmamk_f32 v0, v0, 0x3a800000, v237
	v_rsq_f32_e32 v0, v0
	v_mov_b32_e32 v38, v34
	v_mov_b32_e32 v34, v36
	v_mov_b32_e32 v36, v22
	v_mov_b32_e32 v22, v24
	v_add_u32_e32 v24, 0xa0, v134
	v_mov_b32_e32 v39, v30
	v_mov_b32_e32 v30, v35
	v_mov_b32_e32 v35, v32
	v_mov_b32_e32 v32, v37
	v_mov_b32_e32 v37, v26
	v_mov_b32_e32 v26, v23
	v_mov_b32_e32 v23, v28
	v_mov_b32_e32 v28, v25
	v_mad_i64_i32 v[24:25], s[0:1], v24, s74, v[118:119]
	v_lshl_add_u64 v[40:41], v[24:25], 0, v[120:121]
	v_pk_mul_f32 v[24:25], v[38:39], v[0:1] op_sel_hi:[1,0]
	v_pk_mul_f32 v[30:31], v[30:31], v[0:1] op_sel_hi:[1,0]
	v_pk_mul_f32 v[34:35], v[34:35], v[0:1] op_sel_hi:[1,0]
	v_pk_mul_f32 v[32:33], v[32:33], v[0:1] op_sel_hi:[1,0]
	v_pk_mul_f32 v[36:37], v[36:37], v[0:1] op_sel_hi:[1,0]
	v_pk_mul_f32 v[26:27], v[26:27], v[0:1] op_sel_hi:[1,0]
	v_pk_mul_f32 v[22:23], v[22:23], v[0:1] op_sel_hi:[1,0]
	v_pk_mul_f32 v[28:29], v[28:29], v[0:1] op_sel_hi:[1,0]
	v_mul_f32_e32 v0, 0xbfb8aa3b, v25
	v_mul_f32_e32 v38, 0xbfb8aa3b, v31
	v_mul_f32_e32 v39, 0xbfb8aa3b, v35
	v_mul_f32_e32 v42, 0xbfb8aa3b, v33
	v_mul_f32_e32 v43, 0xbfb8aa3b, v37
	v_mul_f32_e32 v44, 0xbfb8aa3b, v27
	v_mul_f32_e32 v45, 0xbfb8aa3b, v23
	v_mul_f32_e32 v46, 0xbfb8aa3b, v29
	v_exp_f32_e32 v0, v0
	v_exp_f32_e32 v38, v38
	v_exp_f32_e32 v39, v39
	v_exp_f32_e32 v42, v42
	v_exp_f32_e32 v43, v43
	v_exp_f32_e32 v44, v44
	v_exp_f32_e32 v45, v45
	v_exp_f32_e32 v46, v46
	v_add_f32_e32 v0, 1.0, v0
	v_add_f32_e32 v38, 1.0, v38
	v_add_f32_e32 v39, 1.0, v39
	v_add_f32_e32 v42, 1.0, v42
	v_add_f32_e32 v43, 1.0, v43
	v_add_f32_e32 v44, 1.0, v44
	v_add_f32_e32 v45, 1.0, v45
	v_add_f32_e32 v46, 1.0, v46
	v_rcp_f32_e32 v0, v0
	v_rcp_f32_e32 v38, v38
	v_rcp_f32_e32 v39, v39
	v_rcp_f32_e32 v42, v42
	v_rcp_f32_e32 v43, v43
	v_rcp_f32_e32 v44, v44
	v_rcp_f32_e32 v45, v45
	v_rcp_f32_e32 v46, v46
	v_mul_f32_e32 v0, v25, v0
	v_mul_f32_e32 v25, v31, v38
	v_mul_f32_e32 v31, v35, v39
	v_mul_f32_e32 v33, v33, v42
	v_mul_f32_e32 v35, v37, v43
	v_mul_f32_e32 v27, v27, v44
	v_mul_f32_e32 v23, v23, v45
	v_mul_f32_e32 v29, v29, v46
	v_mul_f32_e32 v0, v24, v0
	v_mul_f32_e32 v24, v30, v25
	v_mul_f32_e32 v25, v34, v31
	v_mul_f32_e32 v30, v32, v33
	v_mul_f32_e32 v31, v36, v35
	v_mul_f32_e32 v26, v26, v27
	v_mul_f32_e32 v27, v22, v23
	v_mul_f32_e32 v28, v28, v29
	v_cvt_pk_bf16_f32 v22, v0, v24
	v_cvt_pk_bf16_f32 v23, v25, v30
	v_cvt_pk_bf16_f32 v24, v31, v26
	v_cvt_pk_bf16_f32 v25, v27, v28
	global_store_dwordx4 v[40:41], v[22:25], off
	s_waitcnt vmcnt(7)
	v_mov_b32_e32 v0, v167
	v_fmamk_f32 v0, v0, 0x3a800000, v237
	v_rsq_f32_e32 v0, v0
	v_mov_b32_e32 v22, v18
	v_mov_b32_e32 v18, v20
	v_mov_b32_e32 v20, v6
	v_mov_b32_e32 v6, v8
	v_add_u32_e32 v8, 0xb0, v134
	v_mov_b32_e32 v23, v14
	v_mov_b32_e32 v14, v19
	v_mov_b32_e32 v19, v16
	v_mov_b32_e32 v16, v21
	v_mov_b32_e32 v21, v10
	v_mov_b32_e32 v10, v7
	v_mov_b32_e32 v7, v12
	v_mov_b32_e32 v12, v9
	v_mad_i64_i32 v[8:9], s[0:1], v8, s74, v[118:119]
	v_lshl_add_u64 v[24:25], v[8:9], 0, v[120:121]
	v_pk_mul_f32 v[8:9], v[22:23], v[0:1] op_sel_hi:[1,0]
	v_pk_mul_f32 v[14:15], v[14:15], v[0:1] op_sel_hi:[1,0]
	v_pk_mul_f32 v[18:19], v[18:19], v[0:1] op_sel_hi:[1,0]
	v_pk_mul_f32 v[16:17], v[16:17], v[0:1] op_sel_hi:[1,0]
	v_pk_mul_f32 v[20:21], v[20:21], v[0:1] op_sel_hi:[1,0]
	v_pk_mul_f32 v[10:11], v[10:11], v[0:1] op_sel_hi:[1,0]
	v_pk_mul_f32 v[6:7], v[6:7], v[0:1] op_sel_hi:[1,0]
	v_pk_mul_f32 v[12:13], v[12:13], v[0:1] op_sel_hi:[1,0]
	v_mul_f32_e32 v0, 0xbfb8aa3b, v9
	v_mul_f32_e32 v22, 0xbfb8aa3b, v15
	v_mul_f32_e32 v23, 0xbfb8aa3b, v19
	v_mul_f32_e32 v26, 0xbfb8aa3b, v17
	v_mul_f32_e32 v27, 0xbfb8aa3b, v21
	v_mul_f32_e32 v28, 0xbfb8aa3b, v11
	v_mul_f32_e32 v29, 0xbfb8aa3b, v7
	v_mul_f32_e32 v30, 0xbfb8aa3b, v13
	v_exp_f32_e32 v0, v0
	v_exp_f32_e32 v22, v22
	v_exp_f32_e32 v23, v23
	v_exp_f32_e32 v26, v26
	v_exp_f32_e32 v27, v27
	v_exp_f32_e32 v28, v28
	v_exp_f32_e32 v29, v29
	v_exp_f32_e32 v30, v30
	v_add_f32_e32 v0, 1.0, v0
	v_add_f32_e32 v22, 1.0, v22
	v_add_f32_e32 v23, 1.0, v23
	v_add_f32_e32 v26, 1.0, v26
	v_add_f32_e32 v27, 1.0, v27
	v_add_f32_e32 v28, 1.0, v28
	v_add_f32_e32 v29, 1.0, v29
	v_add_f32_e32 v30, 1.0, v30
	v_rcp_f32_e32 v0, v0
	v_rcp_f32_e32 v22, v22
	v_rcp_f32_e32 v23, v23
	v_rcp_f32_e32 v26, v26
	v_rcp_f32_e32 v27, v27
	v_rcp_f32_e32 v28, v28
	v_rcp_f32_e32 v29, v29
	v_rcp_f32_e32 v30, v30
	v_mul_f32_e32 v0, v9, v0
	v_mul_f32_e32 v9, v15, v22
	v_mul_f32_e32 v15, v19, v23
	v_mul_f32_e32 v17, v17, v26
	v_mul_f32_e32 v19, v21, v27
	v_mul_f32_e32 v11, v11, v28
	v_mul_f32_e32 v7, v7, v29
	v_mul_f32_e32 v13, v13, v30
	v_mul_f32_e32 v0, v8, v0
	v_mul_f32_e32 v8, v14, v9
	v_mul_f32_e32 v9, v18, v15
	s_mov_b64 s[0:1], -1
	v_mul_f32_e32 v14, v16, v17
	v_mul_f32_e32 v15, v20, v19
	v_mul_f32_e32 v10, v10, v11
	v_mul_f32_e32 v11, v6, v7
	v_mul_f32_e32 v12, v12, v13
	v_cvt_pk_bf16_f32 v6, v0, v8
	v_cvt_pk_bf16_f32 v7, v9, v14
	v_cvt_pk_bf16_f32 v8, v15, v10
	v_cvt_pk_bf16_f32 v9, v11, v12
	global_store_dwordx4 v[24:25], v[6:9], off
	s_cbranch_vccnz .LBB0_262
	s_andn2_b64 vcc, exec, s[16:17]
	s_cbranch_vccnz .LBB0_261
	s_barrier

; __device__ __forceinline__ unsigned cvt_pk_bf16(float lo, float hi) { unsigned r; asm volatile("v_cvt_pk_bf16_f32 %0, %1, %2" : "=v"(r) : "v"(lo), "v"(hi)); return r; }
; __device__ __forceinline__ float sigmoidf_(float x) { return __builtin_amdgcn_rcpf(1.f + __builtin_amdgcn_exp2f(-x * LOG2E)); }
;     __device__ __forceinline__ void operator()(const f32x4 (&acc)[2][2][4][2], const pg8::Unit& u, int wr, int wc, int fr, int fq) const {
;     ...
;             for (int m = 0; m < 4; ++m) { const int row = row0 + ai * 128 + m * 16; const float rs = __builtin_amdgcn_rsqf(ss[row] * (1.f / DM) + EPS);
;                 float h[8];
; #pragma unroll
;                 for (int n = 0; n < 2; ++n)
; #pragma unroll
;                     for (int j = 0; j < 4; ++j) { const float g = acc[ai][0][m][n][j] * rs, up = acc[ai][1][m][n][j] * rs; h[4 * n + j] = g * sigmoidf_(g) * up; }
;                 u32x4 w; w.x = cvt_pk_bf16(h[0], h[1]); w.y = cvt_pk_bf16(h[2], h[3]); w.z = cvt_pk_bf16(h[4], h[5]); w.w = cvt_pk_bf16(h[6], h[7]);
;                 *(u32x4*)(H + (size_t)row * DFF + col0) = w; }
.LBB0_1197:
	v_lshl_add_u32 v134, s34, 8, v232
	v_ashrrev_i32_e32 v135, 31, v134
	v_lshl_add_u64 v[136:137], v[134:135], 2, s[14:15]
	global_load_dword v160, v[136:137], off
	global_load_dword v161, v[136:137], off offset:64
	global_load_dword v162, v[136:137], off offset:128
	global_load_dword v163, v[136:137], off offset:192
	global_load_dword v164, v[136:137], off offset:512
	global_load_dword v165, v[136:137], off offset:576
	global_load_dword v166, v[136:137], off offset:640
	global_load_dword v167, v[136:137], off offset:704
	v_lshl_or_b32 v138, s30, 7, v234
	v_mov_b32_e32 v143, v120
	v_mov_b32_e32 v120, v125
	v_mov_b32_e32 v140, v130
	v_mov_b32_e32 v141, v126
	v_mov_b32_e32 v126, v131
	v_mov_b32_e32 v130, v132
	v_mov_b32_e32 v131, v128
	v_mov_b32_e32 v128, v133
	v_mov_b32_e32 v132, v122
	v_mov_b32_e32 v133, v118
	v_mov_b32_e32 v118, v123
	v_mov_b32_e32 v142, v124
	v_mov_b64_e32 v[122:123], s[12:13]
	v_ashrrev_i32_e32 v139, 31, v138
	v_or_b32_e32 v146, 16, v134
	v_mad_i64_i32 v[144:145], s[0:1], v134, s68, v[122:123]
	v_lshlrev_b64 v[124:125], 1, v[138:139]
	v_ashrrev_i32_e32 v147, 31, v146
	v_lshl_add_u64 v[138:139], v[144:145], 0, v[124:125]
	v_lshl_add_u64 v[144:145], v[146:147], 2, s[14:15]
	s_andn2_b64 vcc, exec, s[8:9]
	s_waitcnt vmcnt(7)
	v_mov_b32_e32 v0, v160
	v_fmamk_f32 v0, v0, 0x3a800000, v236
	v_rsq_f32_e32 v0, v0
	s_nop 0
	v_pk_mul_f32 v[120:121], v[120:121], v[0:1] op_sel_hi:[1,0]
	v_pk_mul_f32 v[140:141], v[140:141], v[0:1] op_sel_hi:[1,0]
	v_pk_mul_f32 v[126:127], v[126:127], v[0:1] op_sel_hi:[1,0]
	v_pk_mul_f32 v[130:131], v[130:131], v[0:1] op_sel_hi:[1,0]
	v_pk_mul_f32 v[128:129], v[128:129], v[0:1] op_sel_hi:[1,0]
	v_pk_mul_f32 v[132:133], v[132:133], v[0:1] op_sel_hi:[1,0]
	v_pk_mul_f32 v[118:119], v[118:119], v[0:1] op_sel_hi:[1,0]
	v_pk_mul_f32 v[142:143], v[142:143], v[0:1] op_sel_hi:[1,0]
	v_mul_f32_e32 v152, 0xbfb8aa3b, v121
	v_mul_f32_e32 v0, 0xbfb8aa3b, v141
	v_mul_f32_e32 v135, 0xbfb8aa3b, v127
	v_mul_f32_e32 v147, 0xbfb8aa3b, v131
	v_mul_f32_e32 v148, 0xbfb8aa3b, v129
	v_mul_f32_e32 v149, 0xbfb8aa3b, v133
	v_mul_f32_e32 v150, 0xbfb8aa3b, v119
	v_mul_f32_e32 v151, 0xbfb8aa3b, v143
	v_exp_f32_e32 v152, v152
	v_exp_f32_e32 v0, v0
	v_exp_f32_e32 v135, v135
	v_exp_f32_e32 v147, v147
	v_exp_f32_e32 v148, v148
	v_exp_f32_e32 v149, v149
	v_exp_f32_e32 v150, v150
	v_exp_f32_e32 v151, v151
	v_add_f32_e32 v152, 1.0, v152
	v_add_f32_e32 v0, 1.0, v0
	v_add_f32_e32 v135, 1.0, v135
	v_add_f32_e32 v147, 1.0, v147
	v_add_f32_e32 v148, 1.0, v148
	v_add_f32_e32 v149, 1.0, v149
	v_add_f32_e32 v150, 1.0, v150
	v_add_f32_e32 v151, 1.0, v151
	v_rcp_f32_e32 v152, v152
	v_rcp_f32_e32 v0, v0
	v_rcp_f32_e32 v135, v135
	v_rcp_f32_e32 v147, v147
	v_rcp_f32_e32 v148, v148
	v_rcp_f32_e32 v149, v149
	v_rcp_f32_e32 v150, v150
	v_rcp_f32_e32 v151, v151
	v_mul_f32_e32 v121, v121, v152
	v_mul_f32_e32 v0, v141, v0
	v_mul_f32_e32 v127, v127, v135
	v_mul_f32_e32 v131, v131, v147
	v_mul_f32_e32 v129, v129, v148
	v_mul_f32_e32 v133, v133, v149
	v_mul_f32_e32 v119, v119, v150
	v_mul_f32_e32 v135, v143, v151
	v_mul_f32_e32 v121, v120, v121
	v_mul_f32_e32 v0, v140, v0
	v_mul_f32_e32 v126, v126, v127
	v_mul_f32_e32 v127, v130, v131
	v_mul_f32_e32 v128, v128, v129
	v_mul_f32_e32 v129, v132, v133
	v_mul_f32_e32 v130, v118, v119
	v_mul_f32_e32 v131, v142, v135
	v_cvt_pk_bf16_f32 v118, v0, v126
	v_cvt_pk_bf16_f32 v119, v127, v128
	v_cvt_pk_bf16_f32 v120, v129, v130
	v_cvt_pk_bf16_f32 v121, v131, v121
	global_store_dwordx4 v[138:139], v[118:121], off
	s_waitcnt vmcnt(7)
	v_mov_b32_e32 v0, v161
	v_fmamk_f32 v0, v0, 0x3a800000, v236
	v_rsq_f32_e32 v0, v0
	v_mov_b32_e32 v119, v110
	v_mov_b32_e32 v110, v115
	v_mov_b32_e32 v115, v112
	v_mov_b32_e32 v112, v117
	v_mov_b32_e32 v117, v102
	v_mov_b32_e32 v102, v107
	v_mov_b32_e32 v107, v104
	v_mov_b32_e32 v104, v109
	v_mov_b32_e32 v118, v114
	v_mov_b32_e32 v114, v116
	v_mov_b32_e32 v116, v106
	v_mov_b32_e32 v106, v108
	v_or_b32_e32 v108, 32, v134
	v_pk_mul_f32 v[104:105], v[104:105], v[0:1] op_sel_hi:[1,0]
	v_ashrrev_i32_e32 v109, 31, v108
	v_pk_mul_f32 v[118:119], v[118:119], v[0:1] op_sel_hi:[1,0]
	v_pk_mul_f32 v[110:111], v[110:111], v[0:1] op_sel_hi:[1,0]
	v_pk_mul_f32 v[114:115], v[114:115], v[0:1] op_sel_hi:[1,0]
	v_pk_mul_f32 v[112:113], v[112:113], v[0:1] op_sel_hi:[1,0]
	v_pk_mul_f32 v[116:117], v[116:117], v[0:1] op_sel_hi:[1,0]
	v_pk_mul_f32 v[102:103], v[102:103], v[0:1] op_sel_hi:[1,0]
	v_pk_mul_f32 v[106:107], v[106:107], v[0:1] op_sel_hi:[1,0]
	v_mul_f32_e32 v133, 0xbfb8aa3b, v105
	v_lshl_add_u64 v[126:127], v[108:109], 2, s[14:15]
	v_mul_f32_e32 v0, 0xbfb8aa3b, v119
	v_mul_f32_e32 v109, 0xbfb8aa3b, v111
	v_mul_f32_e32 v128, 0xbfb8aa3b, v115
	v_mul_f32_e32 v129, 0xbfb8aa3b, v113
	v_mul_f32_e32 v130, 0xbfb8aa3b, v117
	v_mul_f32_e32 v131, 0xbfb8aa3b, v103
	v_mul_f32_e32 v132, 0xbfb8aa3b, v107
	v_exp_f32_e32 v133, v133
	v_exp_f32_e32 v0, v0
	v_exp_f32_e32 v109, v109
	v_exp_f32_e32 v128, v128
	v_exp_f32_e32 v129, v129
	v_exp_f32_e32 v130, v130
	v_exp_f32_e32 v131, v131
	v_exp_f32_e32 v132, v132
	v_add_f32_e32 v133, 1.0, v133
	v_add_f32_e32 v0, 1.0, v0
	v_add_f32_e32 v109, 1.0, v109
	v_add_f32_e32 v128, 1.0, v128
	v_add_f32_e32 v129, 1.0, v129
	v_add_f32_e32 v130, 1.0, v130
	v_add_f32_e32 v131, 1.0, v131
	v_add_f32_e32 v132, 1.0, v132
	v_rcp_f32_e32 v133, v133
	v_rcp_f32_e32 v0, v0
	v_rcp_f32_e32 v109, v109
	v_rcp_f32_e32 v128, v128
	v_rcp_f32_e32 v129, v129
	v_rcp_f32_e32 v130, v130
	v_rcp_f32_e32 v131, v131
	v_rcp_f32_e32 v132, v132
	v_mad_i64_i32 v[120:121], s[0:1], v146, s68, v[122:123]
	v_mul_f32_e32 v105, v105, v133
	v_lshl_add_u64 v[120:121], v[120:121], 0, v[124:125]
	v_mul_f32_e32 v0, v119, v0
	v_mul_f32_e32 v109, v111, v109
	v_mul_f32_e32 v111, v115, v128
	v_mul_f32_e32 v113, v113, v129
	v_mul_f32_e32 v115, v117, v130
	v_mul_f32_e32 v103, v103, v131
	v_mul_f32_e32 v107, v107, v132
	v_mul_f32_e32 v105, v104, v105
	v_mul_f32_e32 v0, v118, v0
	v_mul_f32_e32 v109, v110, v109
	v_mul_f32_e32 v110, v114, v111
	v_mul_f32_e32 v111, v112, v113
	v_mul_f32_e32 v112, v116, v115
	v_mul_f32_e32 v113, v102, v103
	v_mul_f32_e32 v106, v106, v107
	v_cvt_pk_bf16_f32 v102, v0, v109
	v_cvt_pk_bf16_f32 v103, v110, v111
	v_cvt_pk_bf16_f32 v104, v112, v113
	v_cvt_pk_bf16_f32 v105, v106, v105
	global_store_dwordx4 v[120:121], v[102:105], off
	s_waitcnt vmcnt(7)
; __device__ __forceinline__ unsigned cvt_pk_bf16(float lo, float hi) { unsigned r; asm volatile("v_cvt_pk_bf16_f32 %0, %1, %2" : "=v"(r) : "v"(lo), "v"(hi)); return r; }
; __device__ __forceinline__ float sigmoidf_(float x) { return __builtin_amdgcn_rcpf(1.f + __builtin_amdgcn_exp2f(-x * LOG2E)); }
;     __device__ __forceinline__ void operator()(const f32x4 (&acc)[2][2][4][2], const pg8::Unit& u, int wr, int wc, int fr, int fq) const {
;         const int row0 = u.pm * 256 + wr * 64 + fr, col0 = u.pn * 128 + wc * 32 + 8 * fq;
; #pragma unroll
;         for (int ai = 0; ai < 2; ++ai)
; #pragma unroll
;             for (int m = 0; m < 4; ++m) { const int row = row0 + ai * 128 + m * 16; const float rs = __builtin_amdgcn_rsqf(ss[row] * (1.f / DM) + EPS);
;                 float h[8];
; #pragma unroll
;                 for (int n = 0; n < 2; ++n)
; #pragma unroll
;                     for (int j = 0; j < 4; ++j) { const float g = acc[ai][0][m][n][j] * rs, up = acc[ai][1][m][n][j] * rs; h[4 * n + j] = g * sigmoidf_(g) * up; }
;                 u32x4 w; w.x = cvt_pk_bf16(h[0], h[1]); w.y = cvt_pk_bf16(h[2], h[3]); w.z = cvt_pk_bf16(h[4], h[5]); w.w = cvt_pk_bf16(h[6], h[7]);
;                 *(u32x4*)(H + (size_t)row * DFF + col0) = w; }
	v_mov_b32_e32 v0, v162
	v_fmamk_f32 v0, v0, 0x3a800000, v236
	v_rsq_f32_e32 v0, v0
	v_mov_b32_e32 v103, v94
	v_mov_b32_e32 v94, v99
	v_mov_b32_e32 v99, v96
	v_mov_b32_e32 v96, v101
	v_mov_b32_e32 v101, v86
	v_mov_b32_e32 v86, v91
	v_mov_b32_e32 v91, v88
	v_mov_b32_e32 v88, v93
	v_mov_b32_e32 v102, v98
	v_mov_b32_e32 v98, v100
	v_mov_b32_e32 v100, v90
	v_mov_b32_e32 v90, v92
	v_or_b32_e32 v92, 48, v134
	v_pk_mul_f32 v[88:89], v[88:89], v[0:1] op_sel_hi:[1,0]
	v_ashrrev_i32_e32 v93, 31, v92
	v_pk_mul_f32 v[102:103], v[102:103], v[0:1] op_sel_hi:[1,0]
	v_pk_mul_f32 v[94:95], v[94:95], v[0:1] op_sel_hi:[1,0]
	v_pk_mul_f32 v[98:99], v[98:99], v[0:1] op_sel_hi:[1,0]
	v_pk_mul_f32 v[96:97], v[96:97], v[0:1] op_sel_hi:[1,0]
	v_pk_mul_f32 v[100:101], v[100:101], v[0:1] op_sel_hi:[1,0]
	v_pk_mul_f32 v[86:87], v[86:87], v[0:1] op_sel_hi:[1,0]
	v_pk_mul_f32 v[90:91], v[90:91], v[0:1] op_sel_hi:[1,0]
	v_mul_f32_e32 v113, 0xbfb8aa3b, v89
	v_mad_i64_i32 v[104:105], s[0:1], v108, s68, v[122:123]
	v_lshl_add_u64 v[106:107], v[92:93], 2, s[14:15]
	v_mul_f32_e32 v0, 0xbfb8aa3b, v103
	v_mul_f32_e32 v93, 0xbfb8aa3b, v95
	v_mul_f32_e32 v108, 0xbfb8aa3b, v99
	v_mul_f32_e32 v109, 0xbfb8aa3b, v97
	v_mul_f32_e32 v110, 0xbfb8aa3b, v101
	v_mul_f32_e32 v111, 0xbfb8aa3b, v87
	v_mul_f32_e32 v112, 0xbfb8aa3b, v91
	v_exp_f32_e32 v113, v113
	v_exp_f32_e32 v0, v0
	v_exp_f32_e32 v93, v93
	v_exp_f32_e32 v108, v108
	v_exp_f32_e32 v109, v109
	v_exp_f32_e32 v110, v110
	v_exp_f32_e32 v111, v111
	v_exp_f32_e32 v112, v112
	v_add_f32_e32 v113, 1.0, v113
	v_add_f32_e32 v0, 1.0, v0
	v_add_f32_e32 v93, 1.0, v93
	v_add_f32_e32 v108, 1.0, v108
	v_add_f32_e32 v109, 1.0, v109
	v_add_f32_e32 v110, 1.0, v110
	v_add_f32_e32 v111, 1.0, v111
	v_add_f32_e32 v112, 1.0, v112
	v_rcp_f32_e32 v113, v113
	v_rcp_f32_e32 v0, v0
	v_rcp_f32_e32 v93, v93
	v_rcp_f32_e32 v108, v108
	v_rcp_f32_e32 v109, v109
	v_rcp_f32_e32 v110, v110
	v_rcp_f32_e32 v111, v111
	v_rcp_f32_e32 v112, v112
	v_mul_f32_e32 v89, v89, v113
	v_lshl_add_u64 v[104:105], v[104:105], 0, v[124:125]
	v_mul_f32_e32 v0, v103, v0
	v_mul_f32_e32 v93, v95, v93
	v_mul_f32_e32 v95, v99, v108
	v_mul_f32_e32 v97, v97, v109
	v_mul_f32_e32 v99, v101, v110
	v_mul_f32_e32 v87, v87, v111
	v_mul_f32_e32 v91, v91, v112
	v_mul_f32_e32 v89, v88, v89
	v_mul_f32_e32 v0, v102, v0
	v_mul_f32_e32 v93, v94, v93
	v_mul_f32_e32 v94, v98, v95
	v_mul_f32_e32 v95, v96, v97
	v_mul_f32_e32 v96, v100, v99
	v_mul_f32_e32 v97, v86, v87
	v_mul_f32_e32 v90, v90, v91
	v_cvt_pk_bf16_f32 v86, v0, v93
	v_cvt_pk_bf16_f32 v87, v94, v95
	v_cvt_pk_bf16_f32 v88, v96, v97
	v_cvt_pk_bf16_f32 v89, v90, v89
	global_store_dwordx4 v[104:105], v[86:89], off
	s_waitcnt vmcnt(7)
	v_mov_b32_e32 v0, v163
	v_fmamk_f32 v0, v0, 0x3a800000, v236
	v_rsq_f32_e32 v0, v0
	v_mov_b32_e32 v86, v82
	v_mov_b32_e32 v87, v78
	v_mov_b32_e32 v78, v83
	v_mov_b32_e32 v82, v84
	v_mov_b32_e32 v83, v80
	v_mov_b32_e32 v80, v85
	v_mov_b32_e32 v84, v70
	v_mov_b32_e32 v85, v74
	v_mov_b32_e32 v74, v71
	v_mov_b32_e32 v70, v72
	v_mov_b32_e32 v71, v76
	v_mov_b32_e32 v76, v73
	v_mad_i64_i32 v[72:73], s[0:1], v92, s68, v[122:123]
	v_lshl_add_u64 v[88:89], v[72:73], 0, v[124:125]
	v_pk_mul_f32 v[72:73], v[86:87], v[0:1] op_sel_hi:[1,0]
	v_pk_mul_f32 v[78:79], v[78:79], v[0:1] op_sel_hi:[1,0]
	v_pk_mul_f32 v[82:83], v[82:83], v[0:1] op_sel_hi:[1,0]
	v_pk_mul_f32 v[80:81], v[80:81], v[0:1] op_sel_hi:[1,0]
	v_pk_mul_f32 v[84:85], v[84:85], v[0:1] op_sel_hi:[1,0]
	v_pk_mul_f32 v[74:75], v[74:75], v[0:1] op_sel_hi:[1,0]
	v_pk_mul_f32 v[70:71], v[70:71], v[0:1] op_sel_hi:[1,0]
	v_pk_mul_f32 v[76:77], v[76:77], v[0:1] op_sel_hi:[1,0]
	v_mul_f32_e32 v0, 0xbfb8aa3b, v73
	v_mul_f32_e32 v86, 0xbfb8aa3b, v79
	v_mul_f32_e32 v87, 0xbfb8aa3b, v83
	v_mul_f32_e32 v90, 0xbfb8aa3b, v81
	v_mul_f32_e32 v91, 0xbfb8aa3b, v85
	v_mul_f32_e32 v92, 0xbfb8aa3b, v75
	v_mul_f32_e32 v93, 0xbfb8aa3b, v71
	v_mul_f32_e32 v94, 0xbfb8aa3b, v77
	v_exp_f32_e32 v0, v0
	v_exp_f32_e32 v86, v86
	v_exp_f32_e32 v87, v87
	v_exp_f32_e32 v90, v90
	v_exp_f32_e32 v91, v91
	v_exp_f32_e32 v92, v92
	v_exp_f32_e32 v93, v93
	v_exp_f32_e32 v94, v94
	v_add_f32_e32 v0, 1.0, v0
	v_add_f32_e32 v86, 1.0, v86
	v_add_f32_e32 v87, 1.0, v87
	v_add_f32_e32 v90, 1.0, v90
	v_add_f32_e32 v91, 1.0, v91
	v_add_f32_e32 v92, 1.0, v92
	v_add_f32_e32 v93, 1.0, v93
	v_add_f32_e32 v94, 1.0, v94
	v_rcp_f32_e32 v0, v0
	v_rcp_f32_e32 v86, v86
	v_rcp_f32_e32 v87, v87
	v_rcp_f32_e32 v90, v90
	v_rcp_f32_e32 v91, v91
	v_rcp_f32_e32 v92, v92
	v_rcp_f32_e32 v93, v93
	v_rcp_f32_e32 v94, v94
	v_mul_f32_e32 v0, v73, v0
	v_mul_f32_e32 v73, v79, v86
	v_mul_f32_e32 v79, v83, v87
	v_mul_f32_e32 v81, v81, v90
	v_mul_f32_e32 v83, v85, v91
	v_mul_f32_e32 v75, v75, v92
	v_mul_f32_e32 v71, v71, v93
	v_mul_f32_e32 v77, v77, v94
	v_mul_f32_e32 v0, v72, v0
	v_mul_f32_e32 v72, v78, v73
	v_mul_f32_e32 v73, v82, v79
	v_mul_f32_e32 v78, v80, v81
	v_mul_f32_e32 v79, v84, v83
	v_mul_f32_e32 v74, v74, v75
	v_mul_f32_e32 v75, v70, v71
	v_mul_f32_e32 v76, v76, v77
	v_cvt_pk_bf16_f32 v70, v0, v72
	v_cvt_pk_bf16_f32 v71, v73, v78
	v_cvt_pk_bf16_f32 v72, v79, v74
	v_cvt_pk_bf16_f32 v73, v75, v76
	global_store_dwordx4 v[88:89], v[70:73], off
	s_waitcnt vmcnt(7)
; __device__ __forceinline__ unsigned cvt_pk_bf16(float lo, float hi) { unsigned r; asm volatile("v_cvt_pk_bf16_f32 %0, %1, %2" : "=v"(r) : "v"(lo), "v"(hi)); return r; }
; __device__ __forceinline__ float sigmoidf_(float x) { return __builtin_amdgcn_rcpf(1.f + __builtin_amdgcn_exp2f(-x * LOG2E)); }
;     __device__ __forceinline__ void operator()(const f32x4 (&acc)[2][2][4][2], const pg8::Unit& u, int wr, int wc, int fr, int fq) const {
;         const int row0 = u.pm * 256 + wr * 64 + fr, col0 = u.pn * 128 + wc * 32 + 8 * fq;
; #pragma unroll
;         for (int ai = 0; ai < 2; ++ai)
; #pragma unroll
;             for (int m = 0; m < 4; ++m) { const int row = row0 + ai * 128 + m * 16; const float rs = __builtin_amdgcn_rsqf(ss[row] * (1.f / DM) + EPS);
;                 float h[8];
; #pragma unroll
;                 for (int n = 0; n < 2; ++n)
; #pragma unroll
;                     for (int j = 0; j < 4; ++j) { const float g = acc[ai][0][m][n][j] * rs, up = acc[ai][1][m][n][j] * rs; h[4 * n + j] = g * sigmoidf_(g) * up; }
;                 u32x4 w; w.x = cvt_pk_bf16(h[0], h[1]); w.y = cvt_pk_bf16(h[2], h[3]); w.z = cvt_pk_bf16(h[4], h[5]); w.w = cvt_pk_bf16(h[6], h[7]);
;                 *(u32x4*)(H + (size_t)row * DFF + col0) = w; }
	v_mov_b32_e32 v0, v164
	v_fmamk_f32 v0, v0, 0x3a800000, v236
	v_rsq_f32_e32 v0, v0
	v_mov_b32_e32 v70, v66
	v_mov_b32_e32 v66, v68
	v_mov_b32_e32 v68, v54
	v_mov_b32_e32 v54, v56
	v_add_u32_e32 v56, 0x80, v134
	v_mov_b32_e32 v71, v62
	v_mov_b32_e32 v62, v67
	v_mov_b32_e32 v67, v64
	v_mov_b32_e32 v64, v69
	v_mov_b32_e32 v69, v58
	v_mov_b32_e32 v58, v55
	v_mov_b32_e32 v55, v60
	v_mov_b32_e32 v60, v57
	v_mad_i64_i32 v[56:57], s[0:1], v56, s68, v[122:123]
	v_lshl_add_u64 v[72:73], v[56:57], 0, v[124:125]
	v_pk_mul_f32 v[56:57], v[70:71], v[0:1] op_sel_hi:[1,0]
	v_pk_mul_f32 v[62:63], v[62:63], v[0:1] op_sel_hi:[1,0]
	v_pk_mul_f32 v[66:67], v[66:67], v[0:1] op_sel_hi:[1,0]
	v_pk_mul_f32 v[64:65], v[64:65], v[0:1] op_sel_hi:[1,0]
	v_pk_mul_f32 v[68:69], v[68:69], v[0:1] op_sel_hi:[1,0]
	v_pk_mul_f32 v[58:59], v[58:59], v[0:1] op_sel_hi:[1,0]
	v_pk_mul_f32 v[54:55], v[54:55], v[0:1] op_sel_hi:[1,0]
	v_pk_mul_f32 v[60:61], v[60:61], v[0:1] op_sel_hi:[1,0]
	v_mul_f32_e32 v0, 0xbfb8aa3b, v57
	v_mul_f32_e32 v70, 0xbfb8aa3b, v63
	v_mul_f32_e32 v71, 0xbfb8aa3b, v67
	v_mul_f32_e32 v74, 0xbfb8aa3b, v65
	v_mul_f32_e32 v75, 0xbfb8aa3b, v69
	v_mul_f32_e32 v76, 0xbfb8aa3b, v59
	v_mul_f32_e32 v77, 0xbfb8aa3b, v55
	v_mul_f32_e32 v78, 0xbfb8aa3b, v61
	v_exp_f32_e32 v0, v0
	v_exp_f32_e32 v70, v70
	v_exp_f32_e32 v71, v71
	v_exp_f32_e32 v74, v74
	v_exp_f32_e32 v75, v75
	v_exp_f32_e32 v76, v76
	v_exp_f32_e32 v77, v77
	v_exp_f32_e32 v78, v78
	v_add_f32_e32 v0, 1.0, v0
	v_add_f32_e32 v70, 1.0, v70
	v_add_f32_e32 v71, 1.0, v71
	v_add_f32_e32 v74, 1.0, v74
	v_add_f32_e32 v75, 1.0, v75
	v_add_f32_e32 v76, 1.0, v76
	v_add_f32_e32 v77, 1.0, v77
	v_add_f32_e32 v78, 1.0, v78
	v_rcp_f32_e32 v0, v0
	v_rcp_f32_e32 v70, v70
	v_rcp_f32_e32 v71, v71
	v_rcp_f32_e32 v74, v74
	v_rcp_f32_e32 v75, v75
	v_rcp_f32_e32 v76, v76
	v_rcp_f32_e32 v77, v77
	v_rcp_f32_e32 v78, v78
	v_mul_f32_e32 v0, v57, v0
	v_mul_f32_e32 v57, v63, v70
	v_mul_f32_e32 v63, v67, v71
	v_mul_f32_e32 v65, v65, v74
	v_mul_f32_e32 v67, v69, v75
	v_mul_f32_e32 v59, v59, v76
	v_mul_f32_e32 v55, v55, v77
	v_mul_f32_e32 v61, v61, v78
	v_mul_f32_e32 v0, v56, v0
	v_mul_f32_e32 v56, v62, v57
	v_mul_f32_e32 v57, v66, v63
	v_mul_f32_e32 v62, v64, v65
	v_mul_f32_e32 v63, v68, v67
	v_mul_f32_e32 v58, v58, v59
	v_mul_f32_e32 v59, v54, v55
	v_mul_f32_e32 v60, v60, v61
	v_cvt_pk_bf16_f32 v54, v0, v56
	v_cvt_pk_bf16_f32 v55, v57, v62
	v_cvt_pk_bf16_f32 v56, v63, v58
	v_cvt_pk_bf16_f32 v57, v59, v60
	global_store_dwordx4 v[72:73], v[54:57], off
	s_waitcnt vmcnt(7)
	v_mov_b32_e32 v0, v165
	v_fmamk_f32 v0, v0, 0x3a800000, v236
	v_rsq_f32_e32 v0, v0
	v_mov_b32_e32 v54, v50
	v_mov_b32_e32 v50, v52
	v_mov_b32_e32 v52, v38
	v_mov_b32_e32 v38, v40
	v_add_u32_e32 v40, 0x90, v134
	v_mov_b32_e32 v55, v46
	v_mov_b32_e32 v46, v51
	v_mov_b32_e32 v51, v48
	v_mov_b32_e32 v48, v53
	v_mov_b32_e32 v53, v42
	v_mov_b32_e32 v42, v39
	v_mov_b32_e32 v39, v44
	v_mov_b32_e32 v44, v41
	v_mad_i64_i32 v[40:41], s[0:1], v40, s68, v[122:123]
	v_lshl_add_u64 v[56:57], v[40:41], 0, v[124:125]
	v_pk_mul_f32 v[40:41], v[54:55], v[0:1] op_sel_hi:[1,0]
	v_pk_mul_f32 v[46:47], v[46:47], v[0:1] op_sel_hi:[1,0]
	v_pk_mul_f32 v[50:51], v[50:51], v[0:1] op_sel_hi:[1,0]
	v_pk_mul_f32 v[48:49], v[48:49], v[0:1] op_sel_hi:[1,0]
	v_pk_mul_f32 v[52:53], v[52:53], v[0:1] op_sel_hi:[1,0]
	v_pk_mul_f32 v[42:43], v[42:43], v[0:1] op_sel_hi:[1,0]
	v_pk_mul_f32 v[38:39], v[38:39], v[0:1] op_sel_hi:[1,0]
	v_pk_mul_f32 v[44:45], v[44:45], v[0:1] op_sel_hi:[1,0]
	v_mul_f32_e32 v0, 0xbfb8aa3b, v41
	v_mul_f32_e32 v54, 0xbfb8aa3b, v47
	v_mul_f32_e32 v55, 0xbfb8aa3b, v51
	v_mul_f32_e32 v58, 0xbfb8aa3b, v49
	v_mul_f32_e32 v59, 0xbfb8aa3b, v53
	v_mul_f32_e32 v60, 0xbfb8aa3b, v43
	v_mul_f32_e32 v61, 0xbfb8aa3b, v39
	v_mul_f32_e32 v62, 0xbfb8aa3b, v45
	v_exp_f32_e32 v0, v0
	v_exp_f32_e32 v54, v54
	v_exp_f32_e32 v55, v55
	v_exp_f32_e32 v58, v58
	v_exp_f32_e32 v59, v59
	v_exp_f32_e32 v60, v60
	v_exp_f32_e32 v61, v61
	v_exp_f32_e32 v62, v62
	v_add_f32_e32 v0, 1.0, v0
	v_add_f32_e32 v54, 1.0, v54
	v_add_f32_e32 v55, 1.0, v55
	v_add_f32_e32 v58, 1.0, v58
	v_add_f32_e32 v59, 1.0, v59
	v_add_f32_e32 v60, 1.0, v60
	v_add_f32_e32 v61, 1.0, v61
	v_add_f32_e32 v62, 1.0, v62
	v_rcp_f32_e32 v0, v0
	v_rcp_f32_e32 v54, v54
	v_rcp_f32_e32 v55, v55
	v_rcp_f32_e32 v58, v58
	v_rcp_f32_e32 v59, v59
	v_rcp_f32_e32 v60, v60
	v_rcp_f32_e32 v61, v61
	v_rcp_f32_e32 v62, v62
	v_mul_f32_e32 v0, v41, v0
	v_mul_f32_e32 v41, v47, v54
	v_mul_f32_e32 v47, v51, v55
	v_mul_f32_e32 v49, v49, v58
	v_mul_f32_e32 v51, v53, v59
	v_mul_f32_e32 v43, v43, v60
	v_mul_f32_e32 v39, v39, v61
	v_mul_f32_e32 v45, v45, v62
	v_mul_f32_e32 v0, v40, v0
	v_mul_f32_e32 v40, v46, v41
	v_mul_f32_e32 v41, v50, v47
	v_mul_f32_e32 v46, v48, v49
	v_mul_f32_e32 v47, v52, v51
	v_mul_f32_e32 v42, v42, v43
	v_mul_f32_e32 v43, v38, v39
	v_mul_f32_e32 v44, v44, v45
	v_cvt_pk_bf16_f32 v38, v0, v40
	v_cvt_pk_bf16_f32 v39, v41, v46
	v_cvt_pk_bf16_f32 v40, v47, v42
	v_cvt_pk_bf16_f32 v41, v43, v44
	global_store_dwordx4 v[56:57], v[38:41], off
	s_waitcnt vmcnt(7)
; __device__ __forceinline__ unsigned cvt_pk_bf16(float lo, float hi) { unsigned r; asm volatile("v_cvt_pk_bf16_f32 %0, %1, %2" : "=v"(r) : "v"(lo), "v"(hi)); return r; }
; #define PG8_BAR __builtin_amdgcn_s_barrier()
; __device__ __forceinline__ float sigmoidf_(float x) { return __builtin_amdgcn_rcpf(1.f + __builtin_amdgcn_exp2f(-x * LOG2E)); }
; template <class Epi, class Sched, bool ALIGN_EPI = false, bool SP2 = false, class Bg = BgNone>
; __device__ __forceinline__ void gemm_phase(PG8_LAS unsigned char* lds, const Gemm g, const Sched& S, const Epi& E, const int wave_sg, const Bg& bg = Bg()) {
;     ...
;         if (!has_next) break;
; #pragma unroll
;         for (int a = 0; a < 2; ++a)
; #pragma unroll
;             for (int b = 0; b < 2; ++b)
; #pragma unroll
;                 for (int m = 0; m < 4; ++m)
; #pragma unroll
;                     for (int n = 0; n < 2; ++n) acc[a][b][m][n] = (f32x4){0.f, 0.f, 0.f, 0.f};
;         cur = nxt; cA = nA; cB = nB; ++ui;
;         if constexpr (ALIGN_EPI) { if (wr == 1) PG8_BAR; }
;     __device__ __forceinline__ void operator()(const f32x4 (&acc)[2][2][4][2], const pg8::Unit& u, int wr, int wc, int fr, int fq) const {
;         const int row0 = u.pm * 256 + wr * 64 + fr, col0 = u.pn * 128 + wc * 32 + 8 * fq;
; #pragma unroll
;         for (int ai = 0; ai < 2; ++ai)
; #pragma unroll
;             for (int m = 0; m < 4; ++m) { const int row = row0 + ai * 128 + m * 16; const float rs = __builtin_amdgcn_rsqf(ss[row] * (1.f / DM) + EPS);
;                 float h[8];
; #pragma unroll
;                 for (int n = 0; n < 2; ++n)
; #pragma unroll
;                     for (int j = 0; j < 4; ++j) { const float g = acc[ai][0][m][n][j] * rs, up = acc[ai][1][m][n][j] * rs; h[4 * n + j] = g * sigmoidf_(g) * up; }
;                 u32x4 w; w.x = cvt_pk_bf16(h[0], h[1]); w.y = cvt_pk_bf16(h[2], h[3]); w.z = cvt_pk_bf16(h[4], h[5]); w.w = cvt_pk_bf16(h[6], h[7]);
;                 *(u32x4*)(H + (size_t)row * DFF + col0) = w; }
	v_mov_b32_e32 v0, v166
	v_fmamk_f32 v0, v0, 0x3a800000, v236
	v_rsq_f32_e32 v0, v0
	v_mov_b32_e32 v38, v34
	v_mov_b32_e32 v34, v36
	v_mov_b32_e32 v36, v22
	v_mov_b32_e32 v22, v24
	v_add_u32_e32 v24, 0xa0, v134
	v_mov_b32_e32 v39, v30
	v_mov_b32_e32 v30, v35
	v_mov_b32_e32 v35, v32
	v_mov_b32_e32 v32, v37
	v_mov_b32_e32 v37, v26
	v_mov_b32_e32 v26, v23
	v_mov_b32_e32 v23, v28
	v_mov_b32_e32 v28, v25
	v_mad_i64_i32 v[24:25], s[0:1], v24, s68, v[122:123]
	v_lshl_add_u64 v[40:41], v[24:25], 0, v[124:125]
	v_pk_mul_f32 v[24:25], v[38:39], v[0:1] op_sel_hi:[1,0]
	v_pk_mul_f32 v[30:31], v[30:31], v[0:1] op_sel_hi:[1,0]
	v_pk_mul_f32 v[34:35], v[34:35], v[0:1] op_sel_hi:[1,0]
	v_pk_mul_f32 v[32:33], v[32:33], v[0:1] op_sel_hi:[1,0]
	v_pk_mul_f32 v[36:37], v[36:37], v[0:1] op_sel_hi:[1,0]
	v_pk_mul_f32 v[26:27], v[26:27], v[0:1] op_sel_hi:[1,0]
	v_pk_mul_f32 v[22:23], v[22:23], v[0:1] op_sel_hi:[1,0]
	v_pk_mul_f32 v[28:29], v[28:29], v[0:1] op_sel_hi:[1,0]
	v_mul_f32_e32 v0, 0xbfb8aa3b, v25
	v_mul_f32_e32 v38, 0xbfb8aa3b, v31
	v_mul_f32_e32 v39, 0xbfb8aa3b, v35
	v_mul_f32_e32 v42, 0xbfb8aa3b, v33
	v_mul_f32_e32 v43, 0xbfb8aa3b, v37
	v_mul_f32_e32 v44, 0xbfb8aa3b, v27
	v_mul_f32_e32 v45, 0xbfb8aa3b, v23
	v_mul_f32_e32 v46, 0xbfb8aa3b, v29
	v_exp_f32_e32 v0, v0
	v_exp_f32_e32 v38, v38
	v_exp_f32_e32 v39, v39
	v_exp_f32_e32 v42, v42
	v_exp_f32_e32 v43, v43
	v_exp_f32_e32 v44, v44
	v_exp_f32_e32 v45, v45
	v_exp_f32_e32 v46, v46
	v_add_f32_e32 v0, 1.0, v0
	v_add_f32_e32 v38, 1.0, v38
	v_add_f32_e32 v39, 1.0, v39
	v_add_f32_e32 v42, 1.0, v42
	v_add_f32_e32 v43, 1.0, v43
	v_add_f32_e32 v44, 1.0, v44
	v_add_f32_e32 v45, 1.0, v45
	v_add_f32_e32 v46, 1.0, v46
	v_rcp_f32_e32 v0, v0
	v_rcp_f32_e32 v38, v38
	v_rcp_f32_e32 v39, v39
	v_rcp_f32_e32 v42, v42
	v_rcp_f32_e32 v43, v43
	v_rcp_f32_e32 v44, v44
	v_rcp_f32_e32 v45, v45
	v_rcp_f32_e32 v46, v46
	v_mul_f32_e32 v0, v25, v0
	v_mul_f32_e32 v25, v31, v38
	v_mul_f32_e32 v31, v35, v39
	v_mul_f32_e32 v33, v33, v42
	v_mul_f32_e32 v35, v37, v43
	v_mul_f32_e32 v27, v27, v44
	v_mul_f32_e32 v23, v23, v45
	v_mul_f32_e32 v29, v29, v46
	v_mul_f32_e32 v0, v24, v0
	v_mul_f32_e32 v24, v30, v25
	v_mul_f32_e32 v25, v34, v31
	v_mul_f32_e32 v30, v32, v33
	v_mul_f32_e32 v31, v36, v35
	v_mul_f32_e32 v26, v26, v27
	v_mul_f32_e32 v27, v22, v23
	v_mul_f32_e32 v28, v28, v29
	v_cvt_pk_bf16_f32 v22, v0, v24
	v_cvt_pk_bf16_f32 v23, v25, v30
	v_cvt_pk_bf16_f32 v24, v31, v26
	v_cvt_pk_bf16_f32 v25, v27, v28
	global_store_dwordx4 v[40:41], v[22:25], off
	s_waitcnt vmcnt(7)
	v_mov_b32_e32 v0, v167
	v_fmamk_f32 v0, v0, 0x3a800000, v236
	v_rsq_f32_e32 v0, v0
	v_mov_b32_e32 v22, v18
	v_mov_b32_e32 v18, v20
	v_mov_b32_e32 v20, v6
	v_mov_b32_e32 v6, v8
	v_add_u32_e32 v8, 0xb0, v134
	v_mov_b32_e32 v23, v14
	v_mov_b32_e32 v14, v19
	v_mov_b32_e32 v19, v16
	v_mov_b32_e32 v16, v21
	v_mov_b32_e32 v21, v10
	v_mov_b32_e32 v10, v7
	v_mov_b32_e32 v7, v12
	v_mov_b32_e32 v12, v9
	v_mad_i64_i32 v[8:9], s[0:1], v8, s68, v[122:123]
	v_lshl_add_u64 v[24:25], v[8:9], 0, v[124:125]
	v_pk_mul_f32 v[8:9], v[22:23], v[0:1] op_sel_hi:[1,0]
	v_pk_mul_f32 v[14:15], v[14:15], v[0:1] op_sel_hi:[1,0]
	v_pk_mul_f32 v[18:19], v[18:19], v[0:1] op_sel_hi:[1,0]
	v_pk_mul_f32 v[16:17], v[16:17], v[0:1] op_sel_hi:[1,0]
	v_pk_mul_f32 v[20:21], v[20:21], v[0:1] op_sel_hi:[1,0]
	v_pk_mul_f32 v[10:11], v[10:11], v[0:1] op_sel_hi:[1,0]
	v_pk_mul_f32 v[6:7], v[6:7], v[0:1] op_sel_hi:[1,0]
	v_pk_mul_f32 v[12:13], v[12:13], v[0:1] op_sel_hi:[1,0]
	v_mul_f32_e32 v0, 0xbfb8aa3b, v9
	v_mul_f32_e32 v22, 0xbfb8aa3b, v15
	v_mul_f32_e32 v23, 0xbfb8aa3b, v19
	v_mul_f32_e32 v26, 0xbfb8aa3b, v17
	v_mul_f32_e32 v27, 0xbfb8aa3b, v21
	v_mul_f32_e32 v28, 0xbfb8aa3b, v11
	v_mul_f32_e32 v29, 0xbfb8aa3b, v7
	v_mul_f32_e32 v30, 0xbfb8aa3b, v13
	v_exp_f32_e32 v0, v0
	v_exp_f32_e32 v22, v22
	v_exp_f32_e32 v23, v23
	v_exp_f32_e32 v26, v26
	v_exp_f32_e32 v27, v27
	v_exp_f32_e32 v28, v28
	v_exp_f32_e32 v29, v29
	v_exp_f32_e32 v30, v30
	v_add_f32_e32 v0, 1.0, v0
	v_add_f32_e32 v22, 1.0, v22
	v_add_f32_e32 v23, 1.0, v23
	v_add_f32_e32 v26, 1.0, v26
	v_add_f32_e32 v27, 1.0, v27
	v_add_f32_e32 v28, 1.0, v28
	v_add_f32_e32 v29, 1.0, v29
	v_add_f32_e32 v30, 1.0, v30
	v_rcp_f32_e32 v0, v0
	v_rcp_f32_e32 v22, v22
	v_rcp_f32_e32 v23, v23
	v_rcp_f32_e32 v26, v26
	v_rcp_f32_e32 v27, v27
	v_rcp_f32_e32 v28, v28
	v_rcp_f32_e32 v29, v29
	v_rcp_f32_e32 v30, v30
	v_mul_f32_e32 v0, v9, v0
	v_mul_f32_e32 v9, v15, v22
	v_mul_f32_e32 v15, v19, v23
	v_mul_f32_e32 v17, v17, v26
	v_mul_f32_e32 v19, v21, v27
	v_mul_f32_e32 v11, v11, v28
	v_mul_f32_e32 v7, v7, v29
	v_mul_f32_e32 v13, v13, v30
	v_mul_f32_e32 v0, v8, v0
	v_mul_f32_e32 v8, v14, v9
	v_mul_f32_e32 v9, v18, v15
	s_mov_b64 s[0:1], -1
	v_mul_f32_e32 v14, v16, v17
	v_mul_f32_e32 v15, v20, v19
	v_mul_f32_e32 v10, v10, v11
	v_mul_f32_e32 v11, v6, v7
	v_mul_f32_e32 v12, v12, v13
	v_cvt_pk_bf16_f32 v6, v0, v8
	v_cvt_pk_bf16_f32 v7, v9, v14
	v_cvt_pk_bf16_f32 v8, v15, v10
	v_cvt_pk_bf16_f32 v9, v11, v12
	global_store_dwordx4 v[24:25], v[6:9], off
	s_cbranch_vccnz .LBB0_1201
	s_andn2_b64 vcc, exec, s[6:7]
	s_cbranch_vccnz .LBB0_1200
	s_barrier
